# attention tile loop: s_setprio 1 over the QK MFMA burst + row-max tree, s_setprio 0 for the exp/PV phase (priority-steered ping-pong of the two waves sharing a SIMD)
# speedup vs baseline: 1.0017x; 1.0017x over previous
.LBB0_509:
	s_setprio 0
	v_exp_f32_e32 v82, v82
	v_exp_f32_e32 v83, v83
	v_exp_f32_e32 v84, v84
	v_exp_f32_e32 v85, v85
	v_exp_f32_e32 v86, v86
	v_exp_f32_e32 v87, v87
	v_exp_f32_e32 v88, v88
	v_exp_f32_e32 v89, v89
	s_waitcnt lgkmcnt(0)
	v_cvt_pk_bf16_f32 v174, v82, v83
	v_cvt_pk_bf16_f32 v175, v84, v85
	v_cvt_pk_bf16_f32 v176, v86, v87
	v_cvt_pk_bf16_f32 v177, v88, v89
	v_add_f32_e32 v190, v82, v83
	v_add_f32_e32 v191, v84, v85
	v_add_f32_e32 v192, v86, v87
	v_add_f32_e32 v193, v88, v89
	v_mfma_f32_32x32x16_bf16 v[50:65], v[126:129], v[174:177], v[50:65]
	v_exp_f32_e32 v90, v90
	v_exp_f32_e32 v91, v91
	v_add_f32_e32 v190, v190, v191
	v_add_f32_e32 v192, v192, v193
	v_mfma_f32_32x32x16_bf16 v[34:49], v[122:125], v[174:177], v[34:49]
	v_exp_f32_e32 v92, v92
	v_exp_f32_e32 v93, v93
	v_cvt_pk_bf16_f32 v178, v90, v91
	v_add_f32_e32 v191, v90, v91
	v_mfma_f32_32x32x16_bf16 v[18:33], v[118:121], v[174:177], v[18:33]
	v_exp_f32_e32 v94, v94
	v_exp_f32_e32 v95, v95
	v_cvt_pk_bf16_f32 v179, v92, v93
	v_add_f32_e32 v193, v92, v93
	v_mfma_f32_32x32x16_bf16 v[2:17], v[114:117], v[174:177], v[2:17]
	v_exp_f32_e32 v96, v96
	v_exp_f32_e32 v97, v97
	v_cvt_pk_bf16_f32 v180, v94, v95
	v_add_f32_e32 v190, v190, v191
	v_add_f32_e32 v191, v94, v95
	v_cvt_pk_bf16_f32 v181, v96, v97
	v_add_f32_e32 v192, v192, v193
	v_add_f32_e32 v193, v96, v97
	v_mfma_f32_32x32x16_bf16 v[50:65], v[110:113], v[178:181], v[50:65]
	v_xor_b32_e32 v172, 64, v156
	v_xor_b32_e32 v0, 0x60, v156
	ds_read_b128 v[82:85], v172
	ds_read_b128 v[86:89], v172 offset:4096
	ds_read_b128 v[90:93], v172 offset:8192
	ds_read_b128 v[94:97], v172 offset:12288
	v_exp_f32_e32 v66, v66
	v_exp_f32_e32 v67, v67
	v_mfma_f32_32x32x16_bf16 v[34:49], v[106:109], v[178:181], v[34:49]
	ds_read_b128 v[156:159], v0
	ds_read_b128 v[160:163], v0 offset:4096
	ds_read_b128 v[164:167], v0 offset:8192
	ds_read_b128 v[168:171], v0 offset:12288
	v_exp_f32_e32 v68, v68
	v_exp_f32_e32 v69, v69
	v_cvt_pk_bf16_f32 v182, v66, v67
	v_add_f32_e32 v190, v190, v191
	v_mfma_f32_32x32x16_bf16 v[18:33], v[102:105], v[178:181], v[18:33]
	v_exp_f32_e32 v70, v70
	v_exp_f32_e32 v71, v71
	v_cvt_pk_bf16_f32 v183, v68, v69
	v_add_f32_e32 v191, v66, v67
	v_add_f32_e32 v192, v192, v193
	v_mfma_f32_32x32x16_bf16 v[2:17], v[98:101], v[178:181], v[2:17]
	v_exp_f32_e32 v72, v72
	v_exp_f32_e32 v73, v73
	v_cvt_pk_bf16_f32 v184, v70, v71
	v_add_f32_e32 v193, v68, v69
	v_add_f32_e32 v190, v190, v191
	v_cvt_pk_bf16_f32 v185, v72, v73
	v_add_f32_e32 v191, v70, v71
	s_waitcnt lgkmcnt(0)
	v_mfma_f32_32x32x16_bf16 v[50:65], v[82:85], v[182:185], v[50:65]
	v_exp_f32_e32 v74, v74
	v_exp_f32_e32 v75, v75
	v_add_f32_e32 v192, v192, v193
	v_add_f32_e32 v193, v72, v73
	v_mfma_f32_32x32x16_bf16 v[34:49], v[86:89], v[182:185], v[34:49]
	v_exp_f32_e32 v76, v76
	v_exp_f32_e32 v77, v77
	v_cvt_pk_bf16_f32 v186, v74, v75
	v_add_f32_e32 v190, v190, v191
	v_mfma_f32_32x32x16_bf16 v[18:33], v[90:93], v[182:185], v[18:33]
	v_exp_f32_e32 v78, v78
	v_exp_f32_e32 v79, v79
	v_cvt_pk_bf16_f32 v187, v76, v77
	v_add_f32_e32 v191, v74, v75
	v_add_f32_e32 v192, v192, v193
	v_mfma_f32_32x32x16_bf16 v[2:17], v[94:97], v[182:185], v[2:17]
	v_exp_f32_e32 v80, v80
	v_exp_f32_e32 v81, v81
	v_cvt_pk_bf16_f32 v188, v78, v79
	v_add_f32_e32 v193, v76, v77
	v_add_f32_e32 v190, v190, v191
	v_cvt_pk_bf16_f32 v189, v80, v81
	v_add_f32_e32 v191, v78, v79
	v_add_f32_e32 v192, v192, v193
	v_mfma_f32_32x32x16_bf16 v[50:65], v[156:159], v[186:189], v[50:65]
	v_add_f32_e32 v193, v80, v81
	v_add_f32_e32 v190, v190, v191
	s_add_i32 s13, s27, 1
	s_cmp_lg_u32 s27, 3
	s_cselect_b32 s27, s13, 0
	s_addk_i32 s26, 0xff00
	s_add_i32 s24, s24, 1
	s_add_i32 s13, s21, s26
	s_sub_i32 s25, s25, 64
	s_add_i32 s23, s23, 64
	v_mfma_f32_32x32x16_bf16 v[34:49], v[160:163], v[186:189], v[34:49]
	v_add_f32_e32 v192, v192, v193
	v_lshl_add_u64 v[130:131], v[130:131], 0, s[56:57]
	v_lshl_add_u64 v[132:133], v[132:133], 0, s[56:57]
	v_mfma_f32_32x32x16_bf16 v[18:33], v[164:167], v[186:189], v[18:33]
	v_add_f32_e32 v190, v190, v192
	v_lshl_add_u64 v[152:153], v[152:153], 0, s[90:91]
	v_mfma_f32_32x32x16_bf16 v[2:17], v[168:171], v[186:189], v[2:17]
	v_add_f32_e32 v155, v155, v190
	s_cmpk_eq_i32 s13, 0xfc00
	s_cbranch_scc1 .LBB0_525
	s_bitcmp1_b32 s24, 0
	s_cbranch_scc0 .Latt_even_entry
	s_mul_i32 s13, s27, 0x6000
	v_add_u32_e32 v0, s13, v205
	v_add_u32_e32 v172, s13, v206
	ds_read_b128 v[174:177], v0
	ds_read_b128 v[190:193], v0 offset:4096
	v_add_u32_e32 v0, s13, v207
	ds_read_b128 v[178:181], v172
	ds_read_b128 v[194:197], v172 offset:4096
	v_add_u32_e32 v172, s13, v208
	ds_read_b128 v[182:185], v0
	ds_read_b128 v[198:201], v0 offset:4096
	ds_read_b128 v[186:189], v172
	ds_read_b128 v[220:223], v172 offset:4096
	s_branch .LBB0_514

.LBB0_514:
	s_cmp_gt_i32 s23, s86
	s_cbranch_scc1 .LBB0_510
	s_mul_i32 s13, s27, 0x6000
	s_add_i32 s13, s13, 0
	s_cmpk_gt_i32 s25, 0x70
	s_cselect_b64 vcc, -1, 0
	s_add_i32 s28, s13, 0x2000
	v_add_u32_e32 v156, s28, v205
	s_setprio 1
